# P7 GEMM k-loop: LDS-DMA issue uses precomputed lane offsets + SGPR bases (no per-k VALU address math or readfirstlane)
# baseline (speedup 1.0000x reference)
.LBB0_212:
	s_andn2_saveexec_b64 s[56:57], s[68:69]
	s_cbranch_execz .LBB0_161
	v_add_u32_e32 v0, 0xfffffc00, v1
	s_mov_b32 s6, 0xfc0fc0fd
	v_mul_hi_u32 v1, v0, s6
	v_lshrrev_b32_e32 v1, 10, v1
	v_mul_u32_u24_e32 v2, 0x410, v1
	v_sub_u32_e32 v2, v0, v2
	v_lshrrev_b32_e32 v67, 3, v2
	v_and_b32_e32 v2, 7, v2
	v_lshl_or_b32 v1, v1, 3, v2
	s_movk_i32 s6, 0x820
	v_add_u32_e32 v2, 8, v1
	v_cmp_gt_u32_e32 vcc, s6, v0
	v_lshlrev_b32_e32 v0, 17, v67
	v_readfirstlane_b32 s6, v91
	v_cndmask_b32_e32 v78, v2, v1, vcc
	v_mov_b32_e32 v1, v97
	v_lshlrev_b32_e32 v96, 7, v78
	v_lshlrev_b64 v[0:1], 1, v[0:1]
	v_add_u32_e32 v8, 0x4000, v91
	v_lshlrev_b64 v[2:3], 11, v[96:97]
	v_lshl_add_u64 v[4:5], v[68:69], 0, v[0:1]
	s_mov_b32 m0, s6
	v_readfirstlane_b32 s6, v8
	v_add_u32_e32 v10, 0x1000, v91
	v_lshl_add_u64 v[6:7], v[70:71], 0, v[2:3]
	global_load_lds_dwordx4 v[4:5], off
	s_mov_b32 m0, s6
	s_mov_b64 s[58:59], 0x10000
	v_readfirstlane_b32 s6, v10
	v_add_u32_e32 v10, 0x5000, v91
	global_load_lds_dwordx4 v[6:7], off
	v_lshl_add_u64 v[8:9], v[4:5], 0, s[58:59]
	s_mov_b32 m0, s6
	v_readfirstlane_b32 s6, v10
	v_add_u32_e32 v10, 0x2000, v91
	global_load_lds_dwordx4 v[8:9], off
	v_lshl_add_u64 v[8:9], v[6:7], 0, s[58:59]
	s_mov_b32 m0, s6
	s_mov_b64 s[58:59], 0x20000
	v_readfirstlane_b32 s6, v10
	v_add_u32_e32 v10, 0x6000, v91
	global_load_lds_dwordx4 v[8:9], off
	v_lshl_add_u64 v[8:9], v[4:5], 0, s[58:59]
	s_mov_b32 m0, s6
	v_readfirstlane_b32 s6, v10
	global_load_lds_dwordx4 v[8:9], off
	v_lshl_add_u64 v[8:9], v[6:7], 0, s[58:59]
	s_mov_b32 m0, s6
	s_mov_b64 s[58:59], 0x30000
	global_load_lds_dwordx4 v[8:9], off
	v_add_u32_e32 v8, 0x3000, v91
	v_lshl_add_u64 v[4:5], v[4:5], 0, s[58:59]
	v_readfirstlane_b32 s6, v8
	s_mov_b32 m0, s6
	v_lshl_add_u64 v[74:75], v[72:73], 0, v[0:1]
	global_load_lds_dwordx4 v[4:5], off
	v_lshl_add_u64 v[4:5], v[6:7], 0, s[58:59]
	v_add_u32_e32 v6, 0x7000, v91
	v_mov_b32_e32 v0, 0
	v_readfirstlane_b32 s6, v6
	s_mov_b32 m0, s6
	s_mov_b64 s[52:53], s[92:93]
	global_load_lds_dwordx4 v[4:5], off
	s_nop 0
	v_lshl_add_u64 v[76:77], v[72:73], 0, v[2:3]
	s_mov_b32 s58, 0
	s_mov_b64 s[6:7], 0
	v_mov_b32_e32 v1, v0
	v_mov_b32_e32 v2, v0
	v_mov_b32_e32 v3, v0
	v_mov_b32_e32 v4, v0
	v_mov_b32_e32 v5, v0
	v_mov_b32_e32 v6, v0
	v_mov_b32_e32 v7, v0
	v_mov_b32_e32 v8, v0
	v_mov_b32_e32 v9, v0
	v_mov_b32_e32 v10, v0
	v_mov_b32_e32 v11, v0
	v_mov_b32_e32 v12, v0
	v_mov_b32_e32 v13, v0
	v_mov_b32_e32 v14, v0
	v_mov_b32_e32 v15, v0
	v_mov_b32_e32 v16, v0
	v_mov_b32_e32 v17, v0
	v_mov_b32_e32 v18, v0
	v_mov_b32_e32 v19, v0
	v_mov_b32_e32 v20, v0
	v_mov_b32_e32 v21, v0
	v_mov_b32_e32 v22, v0
	v_mov_b32_e32 v23, v0
	v_mov_b32_e32 v24, v0
	v_mov_b32_e32 v25, v0
	v_mov_b32_e32 v26, v0
	v_mov_b32_e32 v27, v0
	v_mov_b32_e32 v28, v0
	v_mov_b32_e32 v29, v0
	v_mov_b32_e32 v30, v0
	v_mov_b32_e32 v31, v0
	v_mov_b32_e32 v32, v0
	v_mov_b32_e32 v33, v0
	v_mov_b32_e32 v34, v0
	v_mov_b32_e32 v35, v0
	v_mov_b32_e32 v36, v0
	v_mov_b32_e32 v37, v0
	v_mov_b32_e32 v38, v0
	v_mov_b32_e32 v39, v0
	v_mov_b32_e32 v40, v0
	v_mov_b32_e32 v41, v0
	v_mov_b32_e32 v42, v0
	v_mov_b32_e32 v43, v0
	v_mov_b32_e32 v44, v0
	v_mov_b32_e32 v45, v0
	v_mov_b32_e32 v46, v0
	v_mov_b32_e32 v47, v0
	v_mov_b32_e32 v48, v0
	v_mov_b32_e32 v49, v0
	v_mov_b32_e32 v50, v0
	v_mov_b32_e32 v51, v0
	v_mov_b32_e32 v52, v0
	v_mov_b32_e32 v53, v0
	v_mov_b32_e32 v54, v0
	v_mov_b32_e32 v55, v0
	v_mov_b32_e32 v56, v0
	v_mov_b32_e32 v57, v0
	v_mov_b32_e32 v58, v0
	v_mov_b32_e32 v59, v0
	v_mov_b32_e32 v60, v0
	v_mov_b32_e32 v61, v0
	v_mov_b32_e32 v62, v0
	v_mov_b32_e32 v63, v0
	s_mov_b64 s[88:89], 0x4101080
	s_mov_b64 s[90:91], 0x4111080
	s_mov_b64 s[94:95], 0x4121080
	s_mov_b64 vcc, 0x4131080
	s_mov_b64 s[92:93], 0x13931080
	s_mov_b64 s[38:39], 0x13941080
	s_mov_b64 s[62:63], 0x13951080
	s_mov_b64 s[68:69], 0x13961080
	s_add_i32 s59, s58, 0x8000
	s_and_b32 s60, s59, 0x8000
	v_add_u32_e32 v79, s60, v91
	v_lshl_add_u64 v[80:81], v[74:75], 0, s[6:7]
	v_add_u32_e32 v88, 0x4000, v79
	v_readfirstlane_b32 s60, v79
	v_lshl_add_u64 v[82:83], v[80:81], 0, s[88:89]
	v_lshl_add_u64 v[84:85], v[76:77], 0, s[6:7]
	s_mov_b32 m0, s60
	v_readfirstlane_b32 s60, v88
	v_lshl_add_u64 v[86:87], v[84:85], 0, s[92:93]
	global_load_lds_dwordx4 v[82:83], off
	s_mov_b32 m0, s60
	v_lshl_add_u64 v[82:83], v[80:81], 0, s[90:91]
	global_load_lds_dwordx4 v[86:87], off
	v_add_u32_e32 v86, 0x1000, v79
	s_nop 0
	v_readfirstlane_b32 s60, v86
	v_add_u32_e32 v86, 0x5000, v79
	s_mov_b32 m0, s60
	v_readfirstlane_b32 s60, v86
	v_add_u32_e32 v86, 0x2000, v79
	global_load_lds_dwordx4 v[82:83], off
	v_lshl_add_u64 v[82:83], v[84:85], 0, s[38:39]
	s_mov_b32 m0, s60
	v_readfirstlane_b32 s60, v86
	v_add_u32_e32 v86, 0x6000, v79
	global_load_lds_dwordx4 v[82:83], off
	v_lshl_add_u64 v[82:83], v[80:81], 0, s[94:95]
	s_mov_b32 m0, s60
	v_readfirstlane_b32 s60, v86
	global_load_lds_dwordx4 v[82:83], off
	v_lshl_add_u64 v[82:83], v[84:85], 0, s[62:63]
	s_mov_b32 m0, s60
	v_lshl_add_u64 v[80:81], v[80:81], 0, vcc
	global_load_lds_dwordx4 v[82:83], off
	v_add_u32_e32 v82, 0x3000, v79
	v_add_u32_e32 v79, 0x7000, v79
	v_readfirstlane_b32 s60, v82
	s_mov_b32 m0, s60
	v_readfirstlane_b32 s60, v79
	global_load_lds_dwordx4 v[80:81], off
	v_lshl_add_u64 v[80:81], v[84:85], 0, s[68:69]
	s_mov_b32 m0, s60
	s_nop 0
	global_load_lds_dwordx4 v[80:81], off
	v_readfirstlane_b32 s95, v67
	v_readlane_b32 s88, v254, 11
	v_readlane_b32 s89, v254, 12
	s_lshl_b32 s95, s95, 18
	s_add_u32 s90, s88, 0x13931100
	s_addc_u32 s91, s89, 0
	s_add_u32 s88, s88, 0x4101100
	s_addc_u32 s89, s89, 0
	s_add_u32 s88, s88, s95
	s_addc_u32 s89, s89, 0
	v_readfirstlane_b32 s95, v78
	s_lshl_b32 s95, s95, 18
	s_add_u32 s90, s90, s95
	s_addc_u32 s91, s91, 0
	v_lshrrev_b32_e32 v242, 3, v176
	v_and_b32_e32 v243, 7, v176
	v_bfe_u32 v244, v176, 4, 3
	v_xor_b32_e32 v243, v243, v244
	v_lshlrev_b32_e32 v243, 4, v243
	v_lshl_add_u32 v242, v242, 11, v243
	v_add_u32_e32 v243, 0x10000, v242
	v_add_u32_e32 v244, 0x20000, v242
	v_add_u32_e32 v245, 0x30000, v242
	v_readfirstlane_b32 s94, v91
	s_waitcnt vmcnt(8) lgkmcnt(0)
	s_barrier
.LBB0_214:
	s_add_i32 s59, s58, 0x8000
	s_and_b32 s58, s58, 0x8000
	s_add_i32 s58, s58, 0
	v_add_u32_e32 v79, s58, v95
	v_add_u32_e32 v88, v79, v100
	v_add_u32_e32 v79, v79, v93
	ds_read_b128 v[80:83], v88
	ds_read_b128 v[84:87], v88 offset:2048
	ds_read_b128 v[110:113], v88 offset:4096
	ds_read_b128 v[114:117], v88 offset:6144
	ds_read_b128 v[118:121], v79 offset:16384
	ds_read_b128 v[122:125], v79 offset:18432
	ds_read_b128 v[126:129], v79 offset:20480
	ds_read_b128 v[130:133], v79 offset:22528
	v_add_u32_e32 v206, s58, v101
	v_add_u32_e32 v207, v206, v100
	v_add_u32_e32 v208, v206, v93
	ds_read_b128 v[210:213], v207
	ds_read_b128 v[214:217], v207 offset:2048
	ds_read_b128 v[218:221], v207 offset:4096
	ds_read_b128 v[222:225], v207 offset:6144
	ds_read_b128 v[226:229], v208 offset:16384
	ds_read_b128 v[230:233], v208 offset:18432
	ds_read_b128 v[234:237], v208 offset:20480
	ds_read_b128 v[238:241], v208 offset:22528
	s_setprio 1
	s_waitcnt lgkmcnt(8)
	v_mfma_f32_16x16x32_bf16 v[60:63], v[118:121], v[80:83], v[60:63]
	v_mfma_f32_16x16x32_bf16 v[56:59], v[122:125], v[80:83], v[56:59]
	v_mfma_f32_16x16x32_bf16 v[52:55], v[126:129], v[80:83], v[52:55]
	v_mfma_f32_16x16x32_bf16 v[48:51], v[130:133], v[80:83], v[48:51]
	v_mfma_f32_16x16x32_bf16 v[44:47], v[118:121], v[84:87], v[44:47]
	v_mfma_f32_16x16x32_bf16 v[40:43], v[122:125], v[84:87], v[40:43]
	v_mfma_f32_16x16x32_bf16 v[36:39], v[126:129], v[84:87], v[36:39]
	v_mfma_f32_16x16x32_bf16 v[32:35], v[130:133], v[84:87], v[32:35]
	v_mfma_f32_16x16x32_bf16 v[28:31], v[118:121], v[110:113], v[28:31]
	v_mfma_f32_16x16x32_bf16 v[24:27], v[122:125], v[110:113], v[24:27]
	v_mfma_f32_16x16x32_bf16 v[20:23], v[126:129], v[110:113], v[20:23]
	v_mfma_f32_16x16x32_bf16 v[16:19], v[130:133], v[110:113], v[16:19]
	v_mfma_f32_16x16x32_bf16 v[12:15], v[118:121], v[114:117], v[12:15]
	v_mfma_f32_16x16x32_bf16 v[8:11], v[122:125], v[114:117], v[8:11]
	v_mfma_f32_16x16x32_bf16 v[4:7], v[126:129], v[114:117], v[4:7]
	v_mfma_f32_16x16x32_bf16 v[0:3], v[130:133], v[114:117], v[0:3]
	s_setprio 0
	s_setprio 1
	s_waitcnt lgkmcnt(0)
	s_setprio 0
	s_barrier
	s_add_u32 s6, s6, 0x80
	s_addc_u32 s7, s7, 0
	s_add_u32 s60, s58, s94
	s_add_u32 m0, s60, 0
	s_nop 0
	global_load_lds_dwordx4 v242, s[88:89]
	s_add_u32 m0, s60, 16384
	s_nop 0
	global_load_lds_dwordx4 v242, s[90:91]
	s_add_u32 m0, s60, 4096
	s_nop 0
	global_load_lds_dwordx4 v243, s[88:89]
	s_add_u32 m0, s60, 20480
	s_nop 0
	global_load_lds_dwordx4 v243, s[90:91]
	s_add_u32 m0, s60, 8192
	s_nop 0
	global_load_lds_dwordx4 v244, s[88:89]
	s_add_u32 m0, s60, 24576
	s_nop 0
	global_load_lds_dwordx4 v244, s[90:91]
	s_add_u32 m0, s60, 12288
	s_nop 0
	global_load_lds_dwordx4 v245, s[88:89]
	s_add_u32 m0, s60, 28672
	s_nop 0
	global_load_lds_dwordx4 v245, s[90:91]
	s_add_u32 s88, s88, 0x80
	s_addc_u32 s89, s89, 0
	s_add_u32 s90, s90, 0x80
	s_addc_u32 s91, s91, 0
	s_setprio 1
	v_mfma_f32_16x16x32_bf16 v[60:63], v[226:229], v[210:213], v[60:63]
	v_mfma_f32_16x16x32_bf16 v[56:59], v[230:233], v[210:213], v[56:59]
	v_mfma_f32_16x16x32_bf16 v[52:55], v[234:237], v[210:213], v[52:55]
	v_mfma_f32_16x16x32_bf16 v[48:51], v[238:241], v[210:213], v[48:51]
	v_mfma_f32_16x16x32_bf16 v[44:47], v[226:229], v[214:217], v[44:47]
	v_mfma_f32_16x16x32_bf16 v[40:43], v[230:233], v[214:217], v[40:43]
	v_mfma_f32_16x16x32_bf16 v[36:39], v[234:237], v[214:217], v[36:39]
	v_mfma_f32_16x16x32_bf16 v[32:35], v[238:241], v[214:217], v[32:35]
	v_mfma_f32_16x16x32_bf16 v[28:31], v[226:229], v[218:221], v[28:31]
	v_mfma_f32_16x16x32_bf16 v[24:27], v[230:233], v[218:221], v[24:27]
	v_mfma_f32_16x16x32_bf16 v[20:23], v[234:237], v[218:221], v[20:23]
	v_mfma_f32_16x16x32_bf16 v[16:19], v[238:241], v[218:221], v[16:19]
	v_mfma_f32_16x16x32_bf16 v[12:15], v[226:229], v[222:225], v[12:15]
	v_mfma_f32_16x16x32_bf16 v[8:11], v[230:233], v[222:225], v[8:11]
	v_mfma_f32_16x16x32_bf16 v[4:7], v[234:237], v[222:225], v[4:7]
	v_mfma_f32_16x16x32_bf16 v[0:3], v[238:241], v[222:225], v[0:3]
	s_setprio 0
	s_cmpk_lg_i32 s6, 0x700
	s_mov_b32 s58, s59
	s_waitcnt vmcnt(8)
	s_barrier
	s_cbranch_scc1 .LBB0_214
	s_add_i32 s59, s58, 0x8000
	s_and_b32 s58, s58, 0x8000
	s_add_i32 s58, s58, 0
	v_add_u32_e32 v79, s58, v95
	v_add_u32_e32 v88, v79, v100
	v_add_u32_e32 v79, v79, v93
	ds_read_b128 v[80:83], v88
	ds_read_b128 v[84:87], v88 offset:2048
	ds_read_b128 v[110:113], v88 offset:4096
	ds_read_b128 v[114:117], v88 offset:6144
	ds_read_b128 v[118:121], v79 offset:16384
	ds_read_b128 v[122:125], v79 offset:18432
	ds_read_b128 v[126:129], v79 offset:20480
	ds_read_b128 v[130:133], v79 offset:22528
	v_add_u32_e32 v206, s58, v101
	v_add_u32_e32 v207, v206, v100
	v_add_u32_e32 v208, v206, v93
	ds_read_b128 v[210:213], v207
	ds_read_b128 v[214:217], v207 offset:2048
	ds_read_b128 v[218:221], v207 offset:4096
	ds_read_b128 v[222:225], v207 offset:6144
	ds_read_b128 v[226:229], v208 offset:16384
	ds_read_b128 v[230:233], v208 offset:18432
	ds_read_b128 v[234:237], v208 offset:20480
	ds_read_b128 v[238:241], v208 offset:22528
	s_setprio 1
	s_waitcnt lgkmcnt(8)
	v_mfma_f32_16x16x32_bf16 v[60:63], v[118:121], v[80:83], v[60:63]
	v_mfma_f32_16x16x32_bf16 v[56:59], v[122:125], v[80:83], v[56:59]
	v_mfma_f32_16x16x32_bf16 v[52:55], v[126:129], v[80:83], v[52:55]
	v_mfma_f32_16x16x32_bf16 v[48:51], v[130:133], v[80:83], v[48:51]
	v_mfma_f32_16x16x32_bf16 v[44:47], v[118:121], v[84:87], v[44:47]
	v_mfma_f32_16x16x32_bf16 v[40:43], v[122:125], v[84:87], v[40:43]
	v_mfma_f32_16x16x32_bf16 v[36:39], v[126:129], v[84:87], v[36:39]
	v_mfma_f32_16x16x32_bf16 v[32:35], v[130:133], v[84:87], v[32:35]
	v_mfma_f32_16x16x32_bf16 v[28:31], v[118:121], v[110:113], v[28:31]
	v_mfma_f32_16x16x32_bf16 v[24:27], v[122:125], v[110:113], v[24:27]
	v_mfma_f32_16x16x32_bf16 v[20:23], v[126:129], v[110:113], v[20:23]
	v_mfma_f32_16x16x32_bf16 v[16:19], v[130:133], v[110:113], v[16:19]
	v_mfma_f32_16x16x32_bf16 v[12:15], v[118:121], v[114:117], v[12:15]
	v_mfma_f32_16x16x32_bf16 v[8:11], v[122:125], v[114:117], v[8:11]
	v_mfma_f32_16x16x32_bf16 v[4:7], v[126:129], v[114:117], v[4:7]
	v_mfma_f32_16x16x32_bf16 v[0:3], v[130:133], v[114:117], v[0:3]
	s_setprio 0
	s_setprio 1
	s_waitcnt lgkmcnt(0)
	v_mfma_f32_16x16x32_bf16 v[60:63], v[226:229], v[210:213], v[60:63]
	v_mfma_f32_16x16x32_bf16 v[56:59], v[230:233], v[210:213], v[56:59]
	v_mfma_f32_16x16x32_bf16 v[52:55], v[234:237], v[210:213], v[52:55]
	v_mfma_f32_16x16x32_bf16 v[48:51], v[238:241], v[210:213], v[48:51]
	v_mfma_f32_16x16x32_bf16 v[44:47], v[226:229], v[214:217], v[44:47]
	v_mfma_f32_16x16x32_bf16 v[40:43], v[230:233], v[214:217], v[40:43]
	v_mfma_f32_16x16x32_bf16 v[36:39], v[234:237], v[214:217], v[36:39]
	v_mfma_f32_16x16x32_bf16 v[32:35], v[238:241], v[214:217], v[32:35]
	v_mfma_f32_16x16x32_bf16 v[28:31], v[226:229], v[218:221], v[28:31]
	v_mfma_f32_16x16x32_bf16 v[24:27], v[230:233], v[218:221], v[24:27]
	v_mfma_f32_16x16x32_bf16 v[20:23], v[234:237], v[218:221], v[20:23]
	v_mfma_f32_16x16x32_bf16 v[16:19], v[238:241], v[218:221], v[16:19]
	v_mfma_f32_16x16x32_bf16 v[12:15], v[226:229], v[222:225], v[12:15]
	v_mfma_f32_16x16x32_bf16 v[8:11], v[230:233], v[222:225], v[8:11]
	v_mfma_f32_16x16x32_bf16 v[4:7], v[234:237], v[222:225], v[4:7]
	v_mfma_f32_16x16x32_bf16 v[0:3], v[238:241], v[222:225], v[0:3]
	s_setprio 0
	s_mov_b32 s58, s59
	s_waitcnt vmcnt(0)
	s_barrier
	v_add_u32_e32 v79, v104, v93
	ds_read_b128 v[74:77], v79 offset:55296
	ds_read_b128 v[80:83], v79 offset:53248
	ds_read_b128 v[84:87], v79 offset:51200
	ds_read_b128 v[110:113], v79 offset:49152
	v_add_u32_e32 v79, v104, v100
	ds_read_b128 v[114:117], v79 offset:38912
	ds_read_b128 v[118:121], v79 offset:36864
	ds_read_b128 v[122:125], v79 offset:34816
	ds_read_b128 v[126:129], v79 offset:32768
	s_setprio 1
	s_waitcnt lgkmcnt(0)
	v_mfma_f32_16x16x32_bf16 v[60:63], v[110:113], v[126:129], v[60:63]
	v_mfma_f32_16x16x32_bf16 v[56:59], v[84:87], v[126:129], v[56:59]
	v_mfma_f32_16x16x32_bf16 v[52:55], v[80:83], v[126:129], v[52:55]
	v_mfma_f32_16x16x32_bf16 v[48:51], v[74:77], v[126:129], v[48:51]
	v_mfma_f32_16x16x32_bf16 v[44:47], v[110:113], v[122:125], v[44:47]
	v_mfma_f32_16x16x32_bf16 v[40:43], v[84:87], v[122:125], v[40:43]
	v_mfma_f32_16x16x32_bf16 v[36:39], v[80:83], v[122:125], v[36:39]
	v_mfma_f32_16x16x32_bf16 v[32:35], v[74:77], v[122:125], v[32:35]
	v_mfma_f32_16x16x32_bf16 v[28:31], v[110:113], v[118:121], v[28:31]
	v_mfma_f32_16x16x32_bf16 v[24:27], v[84:87], v[118:121], v[24:27]
	v_mfma_f32_16x16x32_bf16 v[20:23], v[80:83], v[118:121], v[20:23]
	v_mfma_f32_16x16x32_bf16 v[16:19], v[74:77], v[118:121], v[16:19]
	v_mfma_f32_16x16x32_bf16 v[12:15], v[110:113], v[114:117], v[12:15]
	v_mfma_f32_16x16x32_bf16 v[8:11], v[84:87], v[114:117], v[8:11]
	v_mfma_f32_16x16x32_bf16 v[4:7], v[80:83], v[114:117], v[4:7]
	v_mfma_f32_16x16x32_bf16 v[0:3], v[74:77], v[114:117], v[0:3]
	s_setprio 0
	v_add_u32_e32 v79, v105, v100
	ds_read_b128 v[74:77], v79 offset:32768
	ds_read_b128 v[80:83], v79 offset:34816
	ds_read_b128 v[84:87], v79 offset:36864
	ds_read_b128 v[110:113], v79 offset:38912
	v_add_u32_e32 v79, v105, v93
	ds_read_b128 v[114:117], v79 offset:49152
	ds_read_b128 v[118:121], v79 offset:51200
	ds_read_b128 v[122:125], v79 offset:53248
	ds_read_b128 v[126:129], v79 offset:55296
	s_setprio 1
	s_waitcnt lgkmcnt(3)
	v_mfma_f32_16x16x32_bf16 v[60:63], v[114:117], v[74:77], v[60:63]
	s_waitcnt lgkmcnt(2)
	v_mfma_f32_16x16x32_bf16 v[56:59], v[118:121], v[74:77], v[56:59]
	s_waitcnt lgkmcnt(1)
	v_mfma_f32_16x16x32_bf16 v[52:55], v[122:125], v[74:77], v[52:55]
	s_waitcnt lgkmcnt(0)
	v_mfma_f32_16x16x32_bf16 v[48:51], v[126:129], v[74:77], v[48:51]
	v_mfma_f32_16x16x32_bf16 v[44:47], v[114:117], v[80:83], v[44:47]
	v_mfma_f32_16x16x32_bf16 v[40:43], v[118:121], v[80:83], v[40:43]
	v_mfma_f32_16x16x32_bf16 v[36:39], v[122:125], v[80:83], v[36:39]
	v_mfma_f32_16x16x32_bf16 v[32:35], v[126:129], v[80:83], v[32:35]
	v_mfma_f32_16x16x32_bf16 v[28:31], v[114:117], v[84:87], v[28:31]
	v_mfma_f32_16x16x32_bf16 v[24:27], v[118:121], v[84:87], v[24:27]
	v_mfma_f32_16x16x32_bf16 v[20:23], v[122:125], v[84:87], v[20:23]
	v_mfma_f32_16x16x32_bf16 v[16:19], v[126:129], v[84:87], v[16:19]
	v_mfma_f32_16x16x32_bf16 v[12:15], v[114:117], v[110:113], v[12:15]
	v_mfma_f32_16x16x32_bf16 v[8:11], v[118:121], v[110:113], v[8:11]
	v_mfma_f32_16x16x32_bf16 v[4:7], v[122:125], v[110:113], v[4:7]
	v_mfma_f32_16x16x32_bf16 v[0:3], v[126:129], v[110:113], v[0:3]
	s_setprio 0
	s_waitcnt vmcnt(0)
	v_and_b32_e32 v74, 0xfffff8, v78
	v_cmp_ne_u32_e32 vcc, 16, v74
	s_mov_b64 s[6:7], s[0:1]
	s_barrier
	s_and_saveexec_b64 s[58:59], vcc
	s_mov_b64 s[92:93], s[52:53]
	s_cbranch_execz .LBB0_160
	v_readlane_b32 s6, v254, 29
	v_readlane_b32 s7, v254, 30
	v_cmp_lt_u32_e32 vcc, 23, v78
	v_lshlrev_b32_e32 v80, 7, v67
	v_lshl_add_u64 v[74:75], v[96:97], 1, s[6:7]
	v_mul_f32_e32 v83, 0xbfb8aa3b, v60
	v_mul_f32_e32 v84, 0xbfb8aa3b, v61
	v_mul_f32_e32 v79, 0xbfb8aa3b, v62
	v_mul_f32_e32 v82, 0xbfb8aa3b, v63
	v_mul_f32_e32 v126, 0xbfb8aa3b, v56
	v_mul_f32_e32 v127, 0xbfb8aa3b, v57
	v_mul_f32_e32 v124, 0xbfb8aa3b, v58
	v_mul_f32_e32 v125, 0xbfb8aa3b, v59
	v_mul_f32_e32 v122, 0xbfb8aa3b, v52
	v_mul_f32_e32 v123, 0xbfb8aa3b, v53
	v_mul_f32_e32 v120, 0xbfb8aa3b, v54
	v_mul_f32_e32 v121, 0xbfb8aa3b, v55
	v_mul_f32_e32 v118, 0xbfb8aa3b, v48
	v_mul_f32_e32 v119, 0xbfb8aa3b, v49
	v_mul_f32_e32 v116, 0xbfb8aa3b, v50
	v_mul_f32_e32 v117, 0xbfb8aa3b, v51
	v_mul_f32_e32 v114, 0xbfb8aa3b, v44
	v_mul_f32_e32 v115, 0xbfb8aa3b, v45
	v_mul_f32_e32 v112, 0xbfb8aa3b, v46
	v_mul_f32_e32 v113, 0xbfb8aa3b, v47
	v_mul_f32_e32 v110, 0xbfb8aa3b, v40
	v_mul_f32_e32 v111, 0xbfb8aa3b, v41
	v_mul_f32_e32 v67, 0xbfb8aa3b, v42
	v_mul_f32_e32 v109, 0xbfb8aa3b, v43
	s_and_saveexec_b64 s[6:7], vcc
	s_xor_b64 s[60:61], exec, s[6:7]
	s_cbranch_execz .LBB0_218
	v_mov_b32_e32 v40, v97
	s_nop 0
	v_add_u32_e32 v40, v40, v176
	v_ashrrev_i32_e32 v42, 1, v40
	v_and_b32_e32 v41, 64, v40
	v_and_b32_e32 v42, 0xffffffc0, v42
	v_lshrrev_b32_e32 v43, 2, v40
	v_and_or_b32 v40, v40, 15, v80
	v_and_or_b32 v43, v43, 12, v41
	v_add_u32_e32 v42, v40, v42
	v_exp_f32_e32 v44, v83
	v_exp_f32_e32 v45, v79
	v_lshlrev_b32_e32 v96, 1, v43
	v_exp_f32_e32 v46, v84
	v_exp_f32_e32 v47, v82
	v_pk_add_f32 v[44:45], v[44:45], 1.0 op_sel_hi:[1,0]
	s_movk_i32 s67, 0x3200
	v_mad_i64_i32 v[40:41], s[6:7], v42, s67, v[74:75]
	v_lshl_add_u64 v[40:41], v[40:41], 0, v[96:97]
	v_rcp_f32_e32 v43, v44
	s_nop 0
	v_rcp_f32_e32 v48, v45
	v_pk_add_f32 v[44:45], v[46:47], 1.0 op_sel_hi:[1,0]
	s_nop 0
	s_nop 0
	v_rcp_f32_e32 v44, v44
	s_nop 0
	v_rcp_f32_e32 v45, v45
	v_and_b32_sdwa v46, v48, v154 dst_sel:DWORD dst_unused:UNUSED_PAD src0_sel:WORD_1 src1_sel:DWORD
	v_and_b32_sdwa v47, v43, v154 dst_sel:DWORD dst_unused:UNUSED_PAD src0_sel:WORD_1 src1_sel:DWORD
	v_add3_u32 v43, v43, v47, s33
	v_add3_u32 v46, v48, v46, s33
	v_and_b32_sdwa v47, v45, v154 dst_sel:DWORD dst_unused:UNUSED_PAD src0_sel:WORD_1 src1_sel:DWORD
	v_and_b32_sdwa v48, v44, v154 dst_sel:DWORD dst_unused:UNUSED_PAD src0_sel:WORD_1 src1_sel:DWORD
	v_add3_u32 v45, v45, v47, s33
	v_add3_u32 v44, v44, v48, s33
	v_and_b32_e32 v45, 0xffff0000, v45
	v_and_b32_e32 v44, 0xffff0000, v44
	v_or_b32_sdwa v45, v45, v46 dst_sel:DWORD dst_unused:UNUSED_PAD src0_sel:DWORD src1_sel:WORD_1
	v_or_b32_sdwa v44, v44, v43 dst_sel:DWORD dst_unused:UNUSED_PAD src0_sel:DWORD src1_sel:WORD_1
	global_store_dwordx2 v[40:41], v[44:45], off
	v_exp_f32_e32 v44, v126
	v_exp_f32_e32 v45, v124
	v_exp_f32_e32 v46, v127
	v_exp_f32_e32 v47, v125
	v_pk_add_f32 v[44:45], v[44:45], 1.0 op_sel_hi:[1,0]
	s_nop 0
	s_nop 0
	v_rcp_f32_e32 v43, v44
	s_nop 0
	v_rcp_f32_e32 v48, v45
	v_pk_add_f32 v[44:45], v[46:47], 1.0 op_sel_hi:[1,0]
	s_nop 0
	s_nop 0
	v_rcp_f32_e32 v44, v44
	s_nop 0
	v_rcp_f32_e32 v45, v45
	v_and_b32_sdwa v46, v48, v154 dst_sel:DWORD dst_unused:UNUSED_PAD src0_sel:WORD_1 src1_sel:DWORD
	v_and_b32_sdwa v47, v43, v154 dst_sel:DWORD dst_unused:UNUSED_PAD src0_sel:WORD_1 src1_sel:DWORD
	v_add3_u32 v43, v43, v47, s33
	v_add3_u32 v46, v48, v46, s33
	v_and_b32_sdwa v47, v45, v154 dst_sel:DWORD dst_unused:UNUSED_PAD src0_sel:WORD_1 src1_sel:DWORD
	v_and_b32_sdwa v48, v44, v154 dst_sel:DWORD dst_unused:UNUSED_PAD src0_sel:WORD_1 src1_sel:DWORD
	v_add3_u32 v45, v45, v47, s33
	v_add3_u32 v44, v44, v48, s33
	v_and_b32_e32 v45, 0xffff0000, v45
	v_and_b32_e32 v44, 0xffff0000, v44
	v_or_b32_sdwa v45, v45, v46 dst_sel:DWORD dst_unused:UNUSED_PAD src0_sel:DWORD src1_sel:WORD_1
	v_or_b32_sdwa v44, v44, v43 dst_sel:DWORD dst_unused:UNUSED_PAD src0_sel:DWORD src1_sel:WORD_1
	global_store_dwordx2 v[40:41], v[44:45], off offset:32
	v_exp_f32_e32 v44, v122
	v_exp_f32_e32 v45, v120
	v_exp_f32_e32 v46, v123
	v_exp_f32_e32 v47, v121
	v_pk_add_f32 v[44:45], v[44:45], 1.0 op_sel_hi:[1,0]
	s_nop 0
	s_nop 0
	v_rcp_f32_e32 v43, v44
	s_nop 0
	v_rcp_f32_e32 v48, v45
	v_pk_add_f32 v[44:45], v[46:47], 1.0 op_sel_hi:[1,0]
	s_nop 0
	s_nop 0
	v_rcp_f32_e32 v44, v44
	s_nop 0
	v_rcp_f32_e32 v45, v45
	v_and_b32_sdwa v46, v48, v154 dst_sel:DWORD dst_unused:UNUSED_PAD src0_sel:WORD_1 src1_sel:DWORD
	v_and_b32_sdwa v47, v43, v154 dst_sel:DWORD dst_unused:UNUSED_PAD src0_sel:WORD_1 src1_sel:DWORD
	v_add3_u32 v43, v43, v47, s33
	v_add3_u32 v46, v48, v46, s33
	v_and_b32_sdwa v47, v45, v154 dst_sel:DWORD dst_unused:UNUSED_PAD src0_sel:WORD_1 src1_sel:DWORD
	v_and_b32_sdwa v48, v44, v154 dst_sel:DWORD dst_unused:UNUSED_PAD src0_sel:WORD_1 src1_sel:DWORD
	v_add3_u32 v45, v45, v47, s33
	v_add3_u32 v44, v44, v48, s33
	v_and_b32_e32 v45, 0xffff0000, v45
	v_and_b32_e32 v44, 0xffff0000, v44
	v_or_b32_sdwa v45, v45, v46 dst_sel:DWORD dst_unused:UNUSED_PAD src0_sel:DWORD src1_sel:WORD_1
	v_or_b32_sdwa v44, v44, v43 dst_sel:DWORD dst_unused:UNUSED_PAD src0_sel:DWORD src1_sel:WORD_1
	global_store_dwordx2 v[40:41], v[44:45], off offset:64
	v_exp_f32_e32 v44, v118
	v_exp_f32_e32 v45, v116
	v_exp_f32_e32 v46, v119
	v_exp_f32_e32 v47, v117
	v_pk_add_f32 v[44:45], v[44:45], 1.0 op_sel_hi:[1,0]
	s_nop 0
	s_nop 0
	v_rcp_f32_e32 v43, v44
	s_nop 0
	v_rcp_f32_e32 v48, v45
	v_pk_add_f32 v[44:45], v[46:47], 1.0 op_sel_hi:[1,0]
	s_nop 0
	s_nop 0
	v_rcp_f32_e32 v44, v44
	s_nop 0
	v_rcp_f32_e32 v45, v45
	v_and_b32_sdwa v46, v48, v154 dst_sel:DWORD dst_unused:UNUSED_PAD src0_sel:WORD_1 src1_sel:DWORD
	v_and_b32_sdwa v47, v43, v154 dst_sel:DWORD dst_unused:UNUSED_PAD src0_sel:WORD_1 src1_sel:DWORD
	v_add3_u32 v43, v43, v47, s33
	v_add3_u32 v46, v48, v46, s33
	v_and_b32_sdwa v47, v45, v154 dst_sel:DWORD dst_unused:UNUSED_PAD src0_sel:WORD_1 src1_sel:DWORD
	v_and_b32_sdwa v48, v44, v154 dst_sel:DWORD dst_unused:UNUSED_PAD src0_sel:WORD_1 src1_sel:DWORD
	v_add3_u32 v45, v45, v47, s33
	v_add3_u32 v44, v44, v48, s33
	v_and_b32_e32 v45, 0xffff0000, v45
	v_and_b32_e32 v44, 0xffff0000, v44
	v_or_b32_sdwa v45, v45, v46 dst_sel:DWORD dst_unused:UNUSED_PAD src0_sel:DWORD src1_sel:WORD_1
	v_or_b32_sdwa v44, v44, v43 dst_sel:DWORD dst_unused:UNUSED_PAD src0_sel:DWORD src1_sel:WORD_1
	global_store_dwordx2 v[40:41], v[44:45], off offset:96
	v_exp_f32_e32 v44, v114
	v_exp_f32_e32 v45, v112
	v_exp_f32_e32 v46, v115
	v_exp_f32_e32 v47, v113
	v_or_b32_e32 v40, 16, v42
	v_pk_add_f32 v[44:45], v[44:45], 1.0 op_sel_hi:[1,0]
	v_mad_i64_i32 v[40:41], s[6:7], v40, s67, v[74:75]
	v_lshl_add_u64 v[40:41], v[40:41], 0, v[96:97]
	v_mul_f32_e32 v37, 0xbfb8aa3b, v37
	v_mul_f32_e32 v36, 0xbfb8aa3b, v36
	v_rcp_f32_e32 v43, v44
	v_exp_f32_e32 v36, v36
	v_mul_f32_e32 v33, 0xbfb8aa3b, v33
	v_mul_f32_e32 v32, 0xbfb8aa3b, v32
	v_rcp_f32_e32 v48, v45
	v_pk_add_f32 v[44:45], v[46:47], 1.0 op_sel_hi:[1,0]
	v_exp_f32_e32 v32, v32
	s_nop 0
	v_rcp_f32_e32 v44, v44
	s_nop 0
	v_rcp_f32_e32 v45, v45
	v_and_b32_sdwa v46, v48, v154 dst_sel:DWORD dst_unused:UNUSED_PAD src0_sel:WORD_1 src1_sel:DWORD
	v_and_b32_sdwa v47, v43, v154 dst_sel:DWORD dst_unused:UNUSED_PAD src0_sel:WORD_1 src1_sel:DWORD
	v_add3_u32 v43, v43, v47, s33
	v_add3_u32 v46, v48, v46, s33
	v_and_b32_sdwa v47, v45, v154 dst_sel:DWORD dst_unused:UNUSED_PAD src0_sel:WORD_1 src1_sel:DWORD
	v_and_b32_sdwa v48, v44, v154 dst_sel:DWORD dst_unused:UNUSED_PAD src0_sel:WORD_1 src1_sel:DWORD
	v_add3_u32 v45, v45, v47, s33
	v_add3_u32 v44, v44, v48, s33
	v_and_b32_e32 v45, 0xffff0000, v45
	v_and_b32_e32 v44, 0xffff0000, v44
	v_or_b32_sdwa v45, v45, v46 dst_sel:DWORD dst_unused:UNUSED_PAD src0_sel:DWORD src1_sel:WORD_1
	v_or_b32_sdwa v44, v44, v43 dst_sel:DWORD dst_unused:UNUSED_PAD src0_sel:DWORD src1_sel:WORD_1
	global_store_dwordx2 v[40:41], v[44:45], off
	v_exp_f32_e32 v44, v110
	v_exp_f32_e32 v45, v67
	v_exp_f32_e32 v46, v111
	v_exp_f32_e32 v47, v109
	v_pk_add_f32 v[44:45], v[44:45], 1.0 op_sel_hi:[1,0]
	s_nop 0
	s_nop 0
	v_rcp_f32_e32 v43, v44
	s_nop 0
	v_rcp_f32_e32 v48, v45
	v_pk_add_f32 v[44:45], v[46:47], 1.0 op_sel_hi:[1,0]
	s_nop 0
	s_nop 0
	v_rcp_f32_e32 v44, v44
	s_nop 0
	v_rcp_f32_e32 v45, v45
	v_and_b32_sdwa v46, v48, v154 dst_sel:DWORD dst_unused:UNUSED_PAD src0_sel:WORD_1 src1_sel:DWORD
	v_and_b32_sdwa v47, v43, v154 dst_sel:DWORD dst_unused:UNUSED_PAD src0_sel:WORD_1 src1_sel:DWORD
	v_add3_u32 v43, v43, v47, s33
	v_add3_u32 v46, v48, v46, s33
	v_and_b32_sdwa v47, v45, v154 dst_sel:DWORD dst_unused:UNUSED_PAD src0_sel:WORD_1 src1_sel:DWORD
	v_and_b32_sdwa v48, v44, v154 dst_sel:DWORD dst_unused:UNUSED_PAD src0_sel:WORD_1 src1_sel:DWORD
	v_add3_u32 v45, v45, v47, s33
	v_add3_u32 v44, v44, v48, s33
	v_and_b32_e32 v45, 0xffff0000, v45
	v_and_b32_e32 v44, 0xffff0000, v44
	v_or_b32_sdwa v45, v45, v46 dst_sel:DWORD dst_unused:UNUSED_PAD src0_sel:DWORD src1_sel:WORD_1
	v_or_b32_sdwa v44, v44, v43 dst_sel:DWORD dst_unused:UNUSED_PAD src0_sel:DWORD src1_sel:WORD_1
	global_store_dwordx2 v[40:41], v[44:45], off offset:32
	v_exp_f32_e32 v44, v37
	v_mul_f32_e32 v37, 0xbfb8aa3b, v38
	v_exp_f32_e32 v37, v37
	v_mul_f32_e32 v38, 0xbfb8aa3b, v39
	v_exp_f32_e32 v45, v38
	v_pk_add_f32 v[36:37], v[36:37], 1.0 op_sel_hi:[1,0]
	s_nop 0
	s_nop 0
	v_rcp_f32_e32 v38, v36
	s_nop 0
	v_rcp_f32_e32 v39, v37
	v_pk_add_f32 v[36:37], v[44:45], 1.0 op_sel_hi:[1,0]
	s_nop 0
	s_nop 0
	v_rcp_f32_e32 v36, v36
	s_nop 0
	v_rcp_f32_e32 v37, v37
	v_and_b32_sdwa v43, v39, v154 dst_sel:DWORD dst_unused:UNUSED_PAD src0_sel:WORD_1 src1_sel:DWORD
	v_and_b32_sdwa v44, v38, v154 dst_sel:DWORD dst_unused:UNUSED_PAD src0_sel:WORD_1 src1_sel:DWORD
	v_add3_u32 v38, v38, v44, s33
	v_add3_u32 v39, v39, v43, s33
	v_and_b32_sdwa v43, v37, v154 dst_sel:DWORD dst_unused:UNUSED_PAD src0_sel:WORD_1 src1_sel:DWORD
	v_and_b32_sdwa v44, v36, v154 dst_sel:DWORD dst_unused:UNUSED_PAD src0_sel:WORD_1 src1_sel:DWORD
	v_add3_u32 v37, v37, v43, s33
	v_add3_u32 v36, v36, v44, s33
	v_and_b32_e32 v37, 0xffff0000, v37
	v_and_b32_e32 v36, 0xffff0000, v36
	v_or_b32_sdwa v37, v37, v39 dst_sel:DWORD dst_unused:UNUSED_PAD src0_sel:DWORD src1_sel:WORD_1
	v_or_b32_sdwa v36, v36, v38 dst_sel:DWORD dst_unused:UNUSED_PAD src0_sel:DWORD src1_sel:WORD_1
	global_store_dwordx2 v[40:41], v[36:37], off offset:64
	v_exp_f32_e32 v36, v33
	v_mul_f32_e32 v33, 0xbfb8aa3b, v34
	v_exp_f32_e32 v33, v33
	v_mul_f32_e32 v34, 0xbfb8aa3b, v35
	v_exp_f32_e32 v37, v34
	v_pk_add_f32 v[32:33], v[32:33], 1.0 op_sel_hi:[1,0]
	s_nop 0
	s_nop 0
	v_rcp_f32_e32 v34, v32
	s_nop 0
	v_rcp_f32_e32 v35, v33
	v_pk_add_f32 v[32:33], v[36:37], 1.0 op_sel_hi:[1,0]
	s_nop 0
	s_nop 0
	v_rcp_f32_e32 v32, v32
	s_nop 0
	v_rcp_f32_e32 v33, v33
	v_and_b32_sdwa v36, v35, v154 dst_sel:DWORD dst_unused:UNUSED_PAD src0_sel:WORD_1 src1_sel:DWORD
	v_and_b32_sdwa v37, v34, v154 dst_sel:DWORD dst_unused:UNUSED_PAD src0_sel:WORD_1 src1_sel:DWORD
	v_add3_u32 v34, v34, v37, s33
	v_add3_u32 v35, v35, v36, s33
	v_and_b32_sdwa v36, v33, v154 dst_sel:DWORD dst_unused:UNUSED_PAD src0_sel:WORD_1 src1_sel:DWORD
	v_and_b32_sdwa v37, v32, v154 dst_sel:DWORD dst_unused:UNUSED_PAD src0_sel:WORD_1 src1_sel:DWORD
	v_add3_u32 v33, v33, v36, s33
	v_add3_u32 v32, v32, v37, s33
	v_and_b32_e32 v33, 0xffff0000, v33
	v_and_b32_e32 v32, 0xffff0000, v32
	v_or_b32_sdwa v33, v33, v35 dst_sel:DWORD dst_unused:UNUSED_PAD src0_sel:DWORD src1_sel:WORD_1
	v_or_b32_sdwa v32, v32, v34 dst_sel:DWORD dst_unused:UNUSED_PAD src0_sel:DWORD src1_sel:WORD_1
	global_store_dwordx2 v[40:41], v[32:33], off offset:96
	v_mul_f32_e32 v28, 0xbfb8aa3b, v28
	v_exp_f32_e32 v34, v28
	v_mul_f32_e32 v28, 0xbfb8aa3b, v29
	v_exp_f32_e32 v36, v28
	v_mul_f32_e32 v28, 0xbfb8aa3b, v30
	v_exp_f32_e32 v35, v28
	v_or_b32_e32 v32, 32, v42
	v_mad_i64_i32 v[32:33], s[6:7], v32, s67, v[74:75]
	v_mul_f32_e32 v28, 0xbfb8aa3b, v31
	v_pk_add_f32 v[30:31], v[34:35], 1.0 op_sel_hi:[1,0]
	v_exp_f32_e32 v37, v28
	v_lshl_add_u64 v[28:29], v[32:33], 0, v[96:97]
	v_mul_f32_e32 v25, 0xbfb8aa3b, v25
	v_mul_f32_e32 v24, 0xbfb8aa3b, v24
	v_exp_f32_e32 v24, v24
	v_rcp_f32_e32 v32, v30
	v_mul_f32_e32 v21, 0xbfb8aa3b, v21
	v_mul_f32_e32 v20, 0xbfb8aa3b, v20
	v_exp_f32_e32 v20, v20
	v_rcp_f32_e32 v33, v31
	v_pk_add_f32 v[30:31], v[36:37], 1.0 op_sel_hi:[1,0]
	v_mul_f32_e32 v17, 0xbfb8aa3b, v17
	v_mul_f32_e32 v16, 0xbfb8aa3b, v16
	v_exp_f32_e32 v16, v16
	v_rcp_f32_e32 v30, v30
	s_nop 0
	v_rcp_f32_e32 v31, v31
	v_and_b32_sdwa v34, v33, v154 dst_sel:DWORD dst_unused:UNUSED_PAD src0_sel:WORD_1 src1_sel:DWORD
	v_and_b32_sdwa v35, v32, v154 dst_sel:DWORD dst_unused:UNUSED_PAD src0_sel:WORD_1 src1_sel:DWORD
	v_add3_u32 v32, v32, v35, s33
	v_add3_u32 v33, v33, v34, s33
	v_and_b32_sdwa v34, v31, v154 dst_sel:DWORD dst_unused:UNUSED_PAD src0_sel:WORD_1 src1_sel:DWORD
	v_and_b32_sdwa v35, v30, v154 dst_sel:DWORD dst_unused:UNUSED_PAD src0_sel:WORD_1 src1_sel:DWORD
	v_add3_u32 v31, v31, v34, s33
	v_add3_u32 v30, v30, v35, s33
	v_and_b32_e32 v31, 0xffff0000, v31
	v_and_b32_e32 v30, 0xffff0000, v30
	v_or_b32_sdwa v31, v31, v33 dst_sel:DWORD dst_unused:UNUSED_PAD src0_sel:DWORD src1_sel:WORD_1
	v_or_b32_sdwa v30, v30, v32 dst_sel:DWORD dst_unused:UNUSED_PAD src0_sel:DWORD src1_sel:WORD_1
	global_store_dwordx2 v[28:29], v[30:31], off
	v_exp_f32_e32 v30, v25
	v_mul_f32_e32 v25, 0xbfb8aa3b, v26
	v_exp_f32_e32 v25, v25
	v_mul_f32_e32 v26, 0xbfb8aa3b, v27
	v_exp_f32_e32 v31, v26
	v_pk_add_f32 v[24:25], v[24:25], 1.0 op_sel_hi:[1,0]
	s_nop 0
	s_nop 0
	v_rcp_f32_e32 v26, v24
	s_nop 0
	v_rcp_f32_e32 v27, v25
	v_pk_add_f32 v[24:25], v[30:31], 1.0 op_sel_hi:[1,0]
	s_nop 0
	s_nop 0
	v_rcp_f32_e32 v24, v24
	s_nop 0
	v_rcp_f32_e32 v25, v25
	v_and_b32_sdwa v30, v27, v154 dst_sel:DWORD dst_unused:UNUSED_PAD src0_sel:WORD_1 src1_sel:DWORD
	v_and_b32_sdwa v31, v26, v154 dst_sel:DWORD dst_unused:UNUSED_PAD src0_sel:WORD_1 src1_sel:DWORD
	v_add3_u32 v26, v26, v31, s33
	v_add3_u32 v27, v27, v30, s33
	v_and_b32_sdwa v30, v25, v154 dst_sel:DWORD dst_unused:UNUSED_PAD src0_sel:WORD_1 src1_sel:DWORD
	v_and_b32_sdwa v31, v24, v154 dst_sel:DWORD dst_unused:UNUSED_PAD src0_sel:WORD_1 src1_sel:DWORD
	v_add3_u32 v25, v25, v30, s33
	v_add3_u32 v24, v24, v31, s33
	v_and_b32_e32 v25, 0xffff0000, v25
	v_and_b32_e32 v24, 0xffff0000, v24
	v_or_b32_sdwa v25, v25, v27 dst_sel:DWORD dst_unused:UNUSED_PAD src0_sel:DWORD src1_sel:WORD_1
	v_or_b32_sdwa v24, v24, v26 dst_sel:DWORD dst_unused:UNUSED_PAD src0_sel:DWORD src1_sel:WORD_1
	global_store_dwordx2 v[28:29], v[24:25], off offset:32
	v_exp_f32_e32 v24, v21
	v_mul_f32_e32 v21, 0xbfb8aa3b, v22
	v_exp_f32_e32 v21, v21
	v_mul_f32_e32 v22, 0xbfb8aa3b, v23
	v_exp_f32_e32 v25, v22
	v_pk_add_f32 v[20:21], v[20:21], 1.0 op_sel_hi:[1,0]
	s_nop 0
	s_nop 0
	v_rcp_f32_e32 v22, v20
	s_nop 0
	v_rcp_f32_e32 v23, v21
	v_pk_add_f32 v[20:21], v[24:25], 1.0 op_sel_hi:[1,0]
	s_nop 0
	s_nop 0
	v_rcp_f32_e32 v20, v20
	s_nop 0
	v_rcp_f32_e32 v21, v21
	v_and_b32_sdwa v24, v23, v154 dst_sel:DWORD dst_unused:UNUSED_PAD src0_sel:WORD_1 src1_sel:DWORD
	v_and_b32_sdwa v25, v22, v154 dst_sel:DWORD dst_unused:UNUSED_PAD src0_sel:WORD_1 src1_sel:DWORD
	v_add3_u32 v22, v22, v25, s33
	v_add3_u32 v23, v23, v24, s33
	v_and_b32_sdwa v24, v21, v154 dst_sel:DWORD dst_unused:UNUSED_PAD src0_sel:WORD_1 src1_sel:DWORD
	v_and_b32_sdwa v25, v20, v154 dst_sel:DWORD dst_unused:UNUSED_PAD src0_sel:WORD_1 src1_sel:DWORD
	v_add3_u32 v21, v21, v24, s33
	v_add3_u32 v20, v20, v25, s33
	v_and_b32_e32 v21, 0xffff0000, v21
	v_and_b32_e32 v20, 0xffff0000, v20
	v_or_b32_sdwa v21, v21, v23 dst_sel:DWORD dst_unused:UNUSED_PAD src0_sel:DWORD src1_sel:WORD_1
	v_or_b32_sdwa v20, v20, v22 dst_sel:DWORD dst_unused:UNUSED_PAD src0_sel:DWORD src1_sel:WORD_1
	global_store_dwordx2 v[28:29], v[20:21], off offset:64
	v_exp_f32_e32 v20, v17
	v_mul_f32_e32 v17, 0xbfb8aa3b, v18
	v_exp_f32_e32 v17, v17
	v_mul_f32_e32 v18, 0xbfb8aa3b, v19
	v_exp_f32_e32 v21, v18
	v_pk_add_f32 v[16:17], v[16:17], 1.0 op_sel_hi:[1,0]
	s_nop 0
	s_nop 0
	v_rcp_f32_e32 v18, v16
	s_nop 0
	v_rcp_f32_e32 v19, v17
	v_pk_add_f32 v[16:17], v[20:21], 1.0 op_sel_hi:[1,0]
	s_nop 0
	s_nop 0
	v_rcp_f32_e32 v16, v16
	s_nop 0
	v_rcp_f32_e32 v17, v17
	v_and_b32_sdwa v20, v19, v154 dst_sel:DWORD dst_unused:UNUSED_PAD src0_sel:WORD_1 src1_sel:DWORD
	v_and_b32_sdwa v21, v18, v154 dst_sel:DWORD dst_unused:UNUSED_PAD src0_sel:WORD_1 src1_sel:DWORD
	v_add3_u32 v18, v18, v21, s33
	v_add3_u32 v19, v19, v20, s33
	v_and_b32_sdwa v20, v17, v154 dst_sel:DWORD dst_unused:UNUSED_PAD src0_sel:WORD_1 src1_sel:DWORD
	v_and_b32_sdwa v21, v16, v154 dst_sel:DWORD dst_unused:UNUSED_PAD src0_sel:WORD_1 src1_sel:DWORD
	v_add3_u32 v17, v17, v20, s33
	v_add3_u32 v16, v16, v21, s33
	v_and_b32_e32 v17, 0xffff0000, v17
	v_and_b32_e32 v16, 0xffff0000, v16
	v_or_b32_sdwa v17, v17, v19 dst_sel:DWORD dst_unused:UNUSED_PAD src0_sel:DWORD src1_sel:WORD_1
	v_or_b32_sdwa v16, v16, v18 dst_sel:DWORD dst_unused:UNUSED_PAD src0_sel:DWORD src1_sel:WORD_1
	global_store_dwordx2 v[28:29], v[16:17], off offset:96
	v_mul_f32_e32 v12, 0xbfb8aa3b, v12
	v_exp_f32_e32 v18, v12
	v_mul_f32_e32 v12, 0xbfb8aa3b, v13
	v_exp_f32_e32 v20, v12
	v_mul_f32_e32 v12, 0xbfb8aa3b, v14
	v_exp_f32_e32 v19, v12
	v_or_b32_e32 v16, 48, v42
	v_mad_i64_i32 v[16:17], s[6:7], v16, s67, v[74:75]
	v_mul_f32_e32 v12, 0xbfb8aa3b, v15
	v_pk_add_f32 v[14:15], v[18:19], 1.0 op_sel_hi:[1,0]
	v_exp_f32_e32 v21, v12
	v_lshl_add_u64 v[12:13], v[16:17], 0, v[96:97]
	v_mul_f32_e32 v9, 0xbfb8aa3b, v9
	v_mul_f32_e32 v8, 0xbfb8aa3b, v8
	v_exp_f32_e32 v8, v8
	v_rcp_f32_e32 v16, v14
	v_mul_f32_e32 v5, 0xbfb8aa3b, v5
	v_mul_f32_e32 v4, 0xbfb8aa3b, v4
	v_exp_f32_e32 v4, v4
	v_rcp_f32_e32 v17, v15
	v_pk_add_f32 v[14:15], v[20:21], 1.0 op_sel_hi:[1,0]
	v_mul_f32_e32 v0, 0xbfb8aa3b, v0
	v_exp_f32_e32 v0, v0
	v_rcp_f32_e32 v14, v14
	v_add_f32_e32 v0, 1.0, v0
	v_rcp_f32_e32 v15, v15
	v_and_b32_sdwa v18, v17, v154 dst_sel:DWORD dst_unused:UNUSED_PAD src0_sel:WORD_1 src1_sel:DWORD
	v_and_b32_sdwa v19, v16, v154 dst_sel:DWORD dst_unused:UNUSED_PAD src0_sel:WORD_1 src1_sel:DWORD
	v_add3_u32 v16, v16, v19, s33
	v_add3_u32 v17, v17, v18, s33
	v_and_b32_sdwa v18, v15, v154 dst_sel:DWORD dst_unused:UNUSED_PAD src0_sel:WORD_1 src1_sel:DWORD
	v_and_b32_sdwa v19, v14, v154 dst_sel:DWORD dst_unused:UNUSED_PAD src0_sel:WORD_1 src1_sel:DWORD
	v_add3_u32 v15, v15, v18, s33
	v_add3_u32 v14, v14, v19, s33
	v_and_b32_e32 v15, 0xffff0000, v15
	v_and_b32_e32 v14, 0xffff0000, v14
	v_or_b32_sdwa v15, v15, v17 dst_sel:DWORD dst_unused:UNUSED_PAD src0_sel:DWORD src1_sel:WORD_1
	v_or_b32_sdwa v14, v14, v16 dst_sel:DWORD dst_unused:UNUSED_PAD src0_sel:DWORD src1_sel:WORD_1
	global_store_dwordx2 v[12:13], v[14:15], off
	v_exp_f32_e32 v14, v9
	v_mul_f32_e32 v9, 0xbfb8aa3b, v10
	v_exp_f32_e32 v9, v9
	v_mul_f32_e32 v10, 0xbfb8aa3b, v11
	v_exp_f32_e32 v15, v10
	v_pk_add_f32 v[8:9], v[8:9], 1.0 op_sel_hi:[1,0]
	s_nop 0
	s_nop 0
	v_rcp_f32_e32 v10, v8
	s_nop 0
	v_rcp_f32_e32 v11, v9
	v_pk_add_f32 v[8:9], v[14:15], 1.0 op_sel_hi:[1,0]
	s_nop 0
	s_nop 0
	v_rcp_f32_e32 v8, v8
	s_nop 0
	v_rcp_f32_e32 v9, v9
	v_and_b32_sdwa v14, v11, v154 dst_sel:DWORD dst_unused:UNUSED_PAD src0_sel:WORD_1 src1_sel:DWORD
	v_and_b32_sdwa v15, v10, v154 dst_sel:DWORD dst_unused:UNUSED_PAD src0_sel:WORD_1 src1_sel:DWORD
	v_add3_u32 v10, v10, v15, s33
	v_add3_u32 v11, v11, v14, s33
	v_and_b32_sdwa v14, v9, v154 dst_sel:DWORD dst_unused:UNUSED_PAD src0_sel:WORD_1 src1_sel:DWORD
	v_and_b32_sdwa v15, v8, v154 dst_sel:DWORD dst_unused:UNUSED_PAD src0_sel:WORD_1 src1_sel:DWORD
	v_add3_u32 v9, v9, v14, s33
	v_add3_u32 v8, v8, v15, s33
	v_and_b32_e32 v9, 0xffff0000, v9
	v_and_b32_e32 v8, 0xffff0000, v8
	v_or_b32_sdwa v9, v9, v11 dst_sel:DWORD dst_unused:UNUSED_PAD src0_sel:DWORD src1_sel:WORD_1
	v_or_b32_sdwa v8, v8, v10 dst_sel:DWORD dst_unused:UNUSED_PAD src0_sel:DWORD src1_sel:WORD_1
	global_store_dwordx2 v[12:13], v[8:9], off offset:32
	v_exp_f32_e32 v8, v5
	v_mul_f32_e32 v5, 0xbfb8aa3b, v6
	v_exp_f32_e32 v5, v5
	v_mul_f32_e32 v6, 0xbfb8aa3b, v7
	v_exp_f32_e32 v9, v6
	v_pk_add_f32 v[4:5], v[4:5], 1.0 op_sel_hi:[1,0]
	s_nop 0
	s_nop 0
	v_rcp_f32_e32 v6, v4
	s_nop 0
	v_rcp_f32_e32 v7, v5
	v_pk_add_f32 v[4:5], v[8:9], 1.0 op_sel_hi:[1,0]
	s_nop 0
	s_nop 0
	v_rcp_f32_e32 v4, v4
	s_nop 0
	v_rcp_f32_e32 v5, v5
	v_and_b32_sdwa v8, v7, v154 dst_sel:DWORD dst_unused:UNUSED_PAD src0_sel:WORD_1 src1_sel:DWORD
	v_and_b32_sdwa v9, v6, v154 dst_sel:DWORD dst_unused:UNUSED_PAD src0_sel:WORD_1 src1_sel:DWORD
	v_add3_u32 v6, v6, v9, s33
	v_add3_u32 v7, v7, v8, s33
	v_and_b32_sdwa v8, v5, v154 dst_sel:DWORD dst_unused:UNUSED_PAD src0_sel:WORD_1 src1_sel:DWORD
	v_and_b32_sdwa v9, v4, v154 dst_sel:DWORD dst_unused:UNUSED_PAD src0_sel:WORD_1 src1_sel:DWORD
	v_add3_u32 v5, v5, v8, s33
	v_add3_u32 v4, v4, v9, s33
	v_and_b32_e32 v5, 0xffff0000, v5
	v_and_b32_e32 v4, 0xffff0000, v4
	v_or_b32_sdwa v5, v5, v7 dst_sel:DWORD dst_unused:UNUSED_PAD src0_sel:DWORD src1_sel:WORD_1
	v_or_b32_sdwa v4, v4, v6 dst_sel:DWORD dst_unused:UNUSED_PAD src0_sel:DWORD src1_sel:WORD_1
	global_store_dwordx2 v[12:13], v[4:5], off offset:64
	s_nop 0
	v_rcp_f32_e32 v4, v0
	v_mul_f32_e32 v0, 0xbfb8aa3b, v1
	v_exp_f32_e32 v0, v0
	s_nop 0
	v_add_f32_e32 v0, 1.0, v0
	s_nop 0
	v_rcp_f32_e32 v5, v0
	v_mul_f32_e32 v0, 0xbfb8aa3b, v2
	v_exp_f32_e32 v1, v0
	v_mul_f32_e32 v0, 0xbfb8aa3b, v3
	v_exp_f32_e32 v0, v0
	v_bfe_u32 v2, v4, 16, 1
	v_add3_u32 v2, v4, v2, s33
	v_bfe_u32 v3, v5, 16, 1
	v_pk_add_f32 v[0:1], v[0:1], 1.0 op_sel_hi:[1,0]
	v_add3_u32 v3, v5, v3, s33
	v_lshrrev_b32_e32 v2, 16, v2
	v_rcp_f32_e32 v0, v0
	s_mov_b32 s6, 0xffff0000
	v_and_or_b32 v2, v3, s6, v2
	global_store_dword v[12:13], v2, off offset:96
	v_rcp_f32_e32 v1, v1
	s_nop 0
	v_and_b32_sdwa v4, v1, v154 dst_sel:DWORD dst_unused:UNUSED_PAD src0_sel:WORD_1 src1_sel:DWORD
	v_and_b32_sdwa v5, v0, v154 dst_sel:DWORD dst_unused:UNUSED_PAD src0_sel:WORD_1 src1_sel:DWORD
	v_add3_u32 v1, v1, v4, s33
	v_add3_u32 v0, v0, v5, s33
	v_lshrrev_b32_e32 v1, 16, v1
	v_and_or_b32 v81, v0, s6, v1
	s_mov_b64 s[6:7], 0x60
	v_lshl_add_u64 v[76:77], v[12:13], 0, s[6:7]
